# diff-attention pass-1 parking stores: nt instead of write-through sc1 (pass 2 prologue no longer waits for their memory acknowledgement)
# baseline (speedup 1.0000x reference)
.LBB0_1237:
	v_mov_b32_e32 v216, v214
	v_mov_b32_e32 v205, v204
	v_lshl_add_u32 v0, v216, 4, s67
	v_lshl_add_u64 v[2:3], s[28:29], 0, v[0:1]
	v_pk_mul_f32 v[6:7], v[204:205], v[130:131]
	v_pk_mul_f32 v[4:5], v[206:207], v[128:129]
	s_mov_b64 s[2:3], 0x2000
	global_store_dwordx4 v[2:3], v[4:7], off nt
	s_nop 1
	v_pk_mul_f32 v[6:7], v[204:205], v[134:135]
	v_pk_mul_f32 v[4:5], v[206:207], v[132:133]
	v_lshl_add_u64 v[8:9], v[2:3], 0, s[2:3]
	global_store_dwordx4 v[8:9], v[4:7], off nt
	s_nop 1
	s_mov_b64 s[2:3], 0x4000
	v_pk_mul_f32 v[6:7], v[204:205], v[138:139]
	v_pk_mul_f32 v[4:5], v[206:207], v[136:137]
	v_lshl_add_u64 v[8:9], v[2:3], 0, s[2:3]
	global_store_dwordx4 v[8:9], v[4:7], off nt
	s_nop 1
	s_mov_b64 s[2:3], 0x6000
	v_pk_mul_f32 v[6:7], v[204:205], v[142:143]
	v_pk_mul_f32 v[4:5], v[206:207], v[140:141]
	v_lshl_add_u64 v[8:9], v[2:3], 0, s[2:3]
	global_store_dwordx4 v[8:9], v[4:7], off nt
	s_nop 1
	s_mov_b64 s[2:3], 0x8000
	v_pk_mul_f32 v[6:7], v[204:205], v[114:115]
	v_pk_mul_f32 v[4:5], v[206:207], v[112:113]
	v_lshl_add_u64 v[8:9], v[2:3], 0, s[2:3]
	global_store_dwordx4 v[8:9], v[4:7], off nt
	s_nop 1
	s_mov_b64 s[2:3], 0xa000
	v_pk_mul_f32 v[6:7], v[204:205], v[118:119]
	v_pk_mul_f32 v[4:5], v[206:207], v[116:117]
	v_lshl_add_u64 v[8:9], v[2:3], 0, s[2:3]
	global_store_dwordx4 v[8:9], v[4:7], off nt
	s_nop 1
	s_mov_b64 s[2:3], 0xc000
	v_pk_mul_f32 v[6:7], v[204:205], v[122:123]
	v_pk_mul_f32 v[4:5], v[206:207], v[120:121]
	v_lshl_add_u64 v[8:9], v[2:3], 0, s[2:3]
	global_store_dwordx4 v[8:9], v[4:7], off nt
	s_nop 1
	s_mov_b64 s[2:3], 0xe000
	v_pk_mul_f32 v[6:7], v[204:205], v[126:127]
	v_pk_mul_f32 v[4:5], v[206:207], v[124:125]
	v_lshl_add_u64 v[8:9], v[2:3], 0, s[2:3]
	global_store_dwordx4 v[8:9], v[4:7], off nt
	s_nop 1
	s_mov_b64 s[2:3], 0x10000
	v_pk_mul_f32 v[6:7], v[204:205], v[98:99]
	v_pk_mul_f32 v[4:5], v[206:207], v[96:97]
	v_lshl_add_u64 v[8:9], v[2:3], 0, s[2:3]
	global_store_dwordx4 v[8:9], v[4:7], off nt
	s_nop 1
	s_mov_b64 s[2:3], 0x12000
	v_pk_mul_f32 v[6:7], v[204:205], v[102:103]
	v_pk_mul_f32 v[4:5], v[206:207], v[100:101]
	v_lshl_add_u64 v[8:9], v[2:3], 0, s[2:3]
	global_store_dwordx4 v[8:9], v[4:7], off nt
	s_nop 1
	s_mov_b64 s[2:3], 0x14000
	v_pk_mul_f32 v[6:7], v[204:205], v[106:107]
	v_pk_mul_f32 v[4:5], v[206:207], v[104:105]
	v_lshl_add_u64 v[8:9], v[2:3], 0, s[2:3]
	global_store_dwordx4 v[8:9], v[4:7], off nt
	s_nop 1
	s_mov_b64 s[2:3], 0x16000
	v_pk_mul_f32 v[6:7], v[204:205], v[110:111]
	v_pk_mul_f32 v[4:5], v[206:207], v[108:109]
	v_lshl_add_u64 v[8:9], v[2:3], 0, s[2:3]
	global_store_dwordx4 v[8:9], v[4:7], off nt
	s_nop 1
	s_mov_b64 s[2:3], 0x18000
	v_pk_mul_f32 v[6:7], v[204:205], v[82:83]
	v_pk_mul_f32 v[4:5], v[206:207], v[80:81]
	v_lshl_add_u64 v[8:9], v[2:3], 0, s[2:3]
	global_store_dwordx4 v[8:9], v[4:7], off nt
	s_nop 1
	s_mov_b64 s[2:3], 0x1a000
	v_pk_mul_f32 v[6:7], v[204:205], v[86:87]
	v_pk_mul_f32 v[4:5], v[206:207], v[84:85]
	v_lshl_add_u64 v[8:9], v[2:3], 0, s[2:3]
	global_store_dwordx4 v[8:9], v[4:7], off nt
	s_nop 1
	s_mov_b64 s[2:3], 0x1c000
	v_pk_mul_f32 v[6:7], v[204:205], v[90:91]
	v_pk_mul_f32 v[4:5], v[206:207], v[88:89]
	v_lshl_add_u64 v[8:9], v[2:3], 0, s[2:3]
	global_store_dwordx4 v[8:9], v[4:7], off nt
	s_nop 1
	s_mov_b64 s[2:3], 0x1e000
	v_pk_mul_f32 v[6:7], v[204:205], v[94:95]
	v_pk_mul_f32 v[4:5], v[206:207], v[92:93]
	v_lshl_add_u64 v[8:9], v[2:3], 0, s[2:3]
	global_store_dwordx4 v[8:9], v[4:7], off nt
	s_nop 1
	s_mov_b64 s[2:3], 0x20000
	v_pk_mul_f32 v[6:7], v[204:205], v[66:67]
	v_pk_mul_f32 v[4:5], v[206:207], v[64:65]
	v_lshl_add_u64 v[8:9], v[2:3], 0, s[2:3]
	global_store_dwordx4 v[8:9], v[4:7], off nt
	s_nop 1
	s_mov_b64 s[2:3], 0x22000
	v_pk_mul_f32 v[6:7], v[204:205], v[70:71]
	v_pk_mul_f32 v[4:5], v[206:207], v[68:69]
	v_lshl_add_u64 v[8:9], v[2:3], 0, s[2:3]
	global_store_dwordx4 v[8:9], v[4:7], off nt
	s_nop 1
	s_mov_b64 s[2:3], 0x24000
	v_pk_mul_f32 v[6:7], v[204:205], v[74:75]
	v_pk_mul_f32 v[4:5], v[206:207], v[72:73]
	v_lshl_add_u64 v[8:9], v[2:3], 0, s[2:3]
	global_store_dwordx4 v[8:9], v[4:7], off nt
	s_nop 1
	s_mov_b64 s[2:3], 0x26000
	v_pk_mul_f32 v[6:7], v[204:205], v[78:79]
	v_pk_mul_f32 v[4:5], v[206:207], v[76:77]
	v_lshl_add_u64 v[8:9], v[2:3], 0, s[2:3]
	global_store_dwordx4 v[8:9], v[4:7], off nt
	s_nop 1
	s_mov_b64 s[2:3], 0x28000
	v_pk_mul_f32 v[6:7], v[204:205], v[50:51]
	v_pk_mul_f32 v[4:5], v[206:207], v[48:49]
	v_lshl_add_u64 v[8:9], v[2:3], 0, s[2:3]
	global_store_dwordx4 v[8:9], v[4:7], off nt
	s_nop 1
	s_mov_b64 s[2:3], 0x2a000
	v_pk_mul_f32 v[6:7], v[204:205], v[54:55]
	v_pk_mul_f32 v[4:5], v[206:207], v[52:53]
	v_lshl_add_u64 v[8:9], v[2:3], 0, s[2:3]
	global_store_dwordx4 v[8:9], v[4:7], off nt
	s_nop 1
	s_mov_b64 s[2:3], 0x2c000
	v_pk_mul_f32 v[6:7], v[204:205], v[58:59]
	v_pk_mul_f32 v[4:5], v[206:207], v[56:57]
	v_lshl_add_u64 v[8:9], v[2:3], 0, s[2:3]
	global_store_dwordx4 v[8:9], v[4:7], off nt
	s_nop 1
	v_pk_mul_f32 v[6:7], v[204:205], v[62:63]
	v_pk_mul_f32 v[4:5], v[206:207], v[60:61]
	v_lshl_add_u64 v[8:9], v[2:3], 0, s[12:13]
	global_store_dwordx4 v[8:9], v[4:7], off nt
	s_nop 1
	v_pk_mul_f32 v[6:7], v[204:205], v[34:35]
	v_pk_mul_f32 v[4:5], v[206:207], v[32:33]
	v_lshl_add_u64 v[8:9], v[2:3], 0, s[14:15]
	global_store_dwordx4 v[8:9], v[4:7], off nt
	s_nop 1
	v_pk_mul_f32 v[6:7], v[204:205], v[38:39]
	v_pk_mul_f32 v[4:5], v[206:207], v[36:37]
	v_lshl_add_u64 v[8:9], v[2:3], 0, s[16:17]
	global_store_dwordx4 v[8:9], v[4:7], off nt
	s_nop 1
	v_pk_mul_f32 v[6:7], v[204:205], v[42:43]
	v_pk_mul_f32 v[4:5], v[206:207], v[40:41]
	v_lshl_add_u64 v[8:9], v[2:3], 0, s[18:19]
	global_store_dwordx4 v[8:9], v[4:7], off nt
	s_nop 1
	v_pk_mul_f32 v[6:7], v[204:205], v[46:47]
	v_pk_mul_f32 v[4:5], v[206:207], v[44:45]
	v_lshl_add_u64 v[8:9], v[2:3], 0, s[20:21]
	global_store_dwordx4 v[8:9], v[4:7], off nt
	s_nop 1
	v_pk_mul_f32 v[6:7], v[204:205], v[18:19]
	v_pk_mul_f32 v[4:5], v[206:207], v[16:17]
	v_lshl_add_u64 v[8:9], v[2:3], 0, s[22:23]
	global_store_dwordx4 v[8:9], v[4:7], off nt
	s_nop 1
	v_pk_mul_f32 v[6:7], v[204:205], v[22:23]
	v_pk_mul_f32 v[4:5], v[206:207], v[20:21]
	v_lshl_add_u64 v[8:9], v[2:3], 0, s[24:25]
	global_store_dwordx4 v[8:9], v[4:7], off nt
	s_nop 1
	v_pk_mul_f32 v[6:7], v[204:205], v[26:27]
	v_pk_mul_f32 v[4:5], v[206:207], v[24:25]
	v_lshl_add_u64 v[8:9], v[2:3], 0, s[26:27]
	global_store_dwordx4 v[8:9], v[4:7], off nt
	s_nop 1
	v_pk_mul_f32 v[6:7], v[204:205], v[30:31]
	v_pk_mul_f32 v[4:5], v[206:207], v[28:29]
	v_lshl_add_u64 v[2:3], v[2:3], 0, s[30:31]
	global_store_dwordx4 v[2:3], v[4:7], off nt
	s_nop 1
	s_add_u32 s2, s44, s36
	s_addc_u32 s3, s45, s37
	s_mov_b64 s[4:5], -1
	s_and_b64 vcc, exec, s[0:1]
	s_cbranch_vccz .LBB0_1254
	v_mov_b32_e32 v58, v214
	v_mov_b32_e32 v43, v1
	v_ashrrev_i32_e32 v34, 4, v58
	v_add_u32_e32 v42, 4, v34
	v_lshlrev_b32_e32 v59, 4, v58
	v_add_u32_e32 v2, s66, v34
	v_add_u32_e32 v4, s66, v42
	v_and_b32_e32 v0, 0xf0, v59
	v_ashrrev_i32_e32 v3, 31, v2
	v_ashrrev_i32_e32 v5, 31, v4
	v_lshl_add_u64 v[30:31], s[42:43], 0, v[0:1]
	v_lshlrev_b64 v[2:3], 14, v[2:3]
	v_lshlrev_b64 v[4:5], 14, v[4:5]
	v_lshl_add_u64 v[2:3], v[30:31], 0, v[2:3]
	v_lshl_add_u64 v[6:7], v[30:31], 0, v[4:5]
	global_load_dwordx4 v[2:5], v[2:3], off
	s_nop 0
	global_load_dwordx4 v[6:9], v[6:7], off
	v_add_u32_e32 v60, 8, v34
	v_add_u32_e32 v10, s66, v60
	v_ashrrev_i32_e32 v11, 31, v10
	v_lshlrev_b64 v[10:11], 14, v[10:11]
	v_lshl_add_u64 v[10:11], v[30:31], 0, v[10:11]
	v_add_u32_e32 v61, 12, v34
	global_load_dwordx4 v[10:13], v[10:11], off
	v_add_u32_e32 v14, s66, v61
	v_ashrrev_i32_e32 v15, 31, v14
	v_add_u32_e32 v62, 16, v34
	v_lshlrev_b64 v[14:15], 14, v[14:15]
	v_add_u32_e32 v18, s66, v62
	v_lshl_add_u64 v[14:15], v[30:31], 0, v[14:15]
	v_ashrrev_i32_e32 v19, 31, v18
	global_load_dwordx4 v[14:17], v[14:15], off
	v_lshlrev_b64 v[18:19], 14, v[18:19]
	v_add_u32_e32 v63, 20, v34
	v_lshl_add_u64 v[18:19], v[30:31], 0, v[18:19]
	v_add_u32_e32 v22, s66, v63
	global_load_dwordx4 v[18:21], v[18:19], off
	v_ashrrev_i32_e32 v23, 31, v22
	v_lshlrev_b64 v[22:23], 14, v[22:23]
	v_add_u32_e32 v64, 24, v34
	v_lshl_add_u64 v[22:23], v[30:31], 0, v[22:23]
	v_add_u32_e32 v26, s66, v64
	global_load_dwordx4 v[22:25], v[22:23], off
	v_ashrrev_i32_e32 v27, 31, v26
	v_add_u32_e32 v65, 28, v34
	v_lshlrev_b64 v[26:27], 14, v[26:27]
	v_add_u32_e32 v32, s66, v65
	v_lshl_add_u64 v[26:27], v[30:31], 0, v[26:27]
	v_ashrrev_i32_e32 v33, 31, v32
	global_load_dwordx4 v[26:29], v[26:27], off
	v_lshlrev_b64 v[32:33], 14, v[32:33]
	v_lshl_add_u64 v[30:31], v[30:31], 0, v[32:33]
	global_load_dwordx4 v[30:33], v[30:31], off
	v_add_u32_e32 v66, s65, v58
	v_ashrrev_i32_e32 v46, 4, v66
	v_ashrrev_i32_e32 v47, 31, v46
	v_lshlrev_b32_e32 v67, 3, v58
	v_xor_b32_e32 v45, v34, v58
	v_lshlrev_b64 v[48:49], 14, v[46:47]
	v_ashrrev_i32_e32 v52, 5, v66
	v_lshlrev_b32_e32 v44, 8, v34
	v_lshl_add_u64 v[34:35], s[2:3], 0, v[48:49]
	v_and_b32_e32 v47, 0xf8, v67
	v_lshlrev_b32_e32 v45, 4, v45
	v_xor_b32_e32 v54, v42, v58
	v_ashrrev_i32_e32 v53, 31, v52
	v_lshl_add_u64 v[50:51], v[34:35], 0, v[0:1]
	v_lshlrev_b32_e32 v68, 8, v42
	v_lshlrev_b32_e32 v42, 1, v47
	v_and_b32_e32 v47, 0xf0, v45
	v_lshlrev_b32_e32 v69, 4, v54
	v_lshlrev_b64 v[54:55], 14, v[52:53]
	v_add_co_u32_e32 v38, vcc, s52, v50
	v_add3_u32 v53, s91, v44, v47
	v_lshl_add_u64 v[44:45], s[40:41], 0, v[54:55]
	v_addc_co_u32_e32 v39, vcc, 0, v51, vcc
	v_lshl_add_u64 v[56:57], v[44:45], 0, v[42:43]
	global_load_dwordx4 v[34:37], v[50:51], off
	s_nop 0
	global_load_dwordx4 v[38:41], v[38:39], off
	v_and_b32_e32 v69, 0xf0, v69
	global_load_dwordx4 v[42:45], v[56:57], off
	v_add3_u32 v68, s91, v68, v69
	s_add_u32 s6, s76, s36
	s_addc_u32 s7, s77, s37
	v_cmp_gt_u32_e64 s[4:5], 32, v58
	s_mov_b32 s48, 0
	s_waitcnt vmcnt(10)
	ds_write_b128 v53, v[2:5]
	s_waitcnt vmcnt(9)
	ds_write_b128 v68, v[6:9]
	v_add_co_u32_e32 v2, vcc, s85, v56
	v_xor_b32_e32 v6, v60, v58
	s_nop 0
	v_addc_co_u32_e32 v3, vcc, 0, v57, vcc
	global_load_dwordx4 v[2:5], v[2:3], off
	v_lshlrev_b32_e32 v6, 4, v6
	v_lshlrev_b32_e32 v53, 8, v60
	v_and_b32_e32 v60, 0xf0, v6
	v_add_co_u32_e32 v6, vcc, s52, v56
	v_add3_u32 v53, s91, v53, v60
	s_nop 0
	v_addc_co_u32_e32 v7, vcc, 0, v57, vcc
	global_load_dwordx4 v[6:9], v[6:7], off
	s_waitcnt vmcnt(10)
	ds_write_b128 v53, v[10:13]
	v_xor_b32_e32 v11, v61, v58
	v_lshlrev_b32_e32 v11, 4, v11
	v_lshlrev_b32_e32 v10, 8, v61
	v_and_b32_e32 v11, 0xf0, v11
	v_add3_u32 v10, s91, v10, v11
	s_waitcnt vmcnt(9)
	ds_write_b128 v10, v[14:17]
	v_lshlrev_b32_e32 v10, 8, v62
	v_xor_b32_e32 v11, v63, v58
	v_add3_u32 v10, s91, v10, v47
	v_lshlrev_b32_e32 v11, 4, v11
	s_waitcnt vmcnt(8)
	ds_write_b128 v10, v[18:21]
	v_lshlrev_b32_e32 v10, 8, v63
	v_and_b32_e32 v11, 0xf0, v11
	v_add3_u32 v10, s91, v10, v11
	v_xor_b32_e32 v11, v64, v58
	v_lshlrev_b32_e32 v11, 4, v11
	s_waitcnt vmcnt(7)
	ds_write_b128 v10, v[22:25]
	v_lshlrev_b32_e32 v10, 8, v64
	v_and_b32_e32 v11, 0xf0, v11
	v_add3_u32 v10, s91, v10, v11
	v_xor_b32_e32 v11, v65, v58
	v_lshlrev_b32_e32 v11, 4, v11
	s_waitcnt vmcnt(6)
	ds_write_b128 v10, v[26:29]
	v_lshlrev_b32_e32 v10, 8, v65
	v_and_b32_e32 v11, 0xf0, v11
	v_add3_u32 v10, s91, v10, v11
	s_waitcnt vmcnt(5)
	ds_write_b128 v10, v[30:33]
	v_and_b32_e32 v15, 24, v67
	v_and_b32_e32 v16, 0xc0, v59
	v_lshlrev_b32_e32 v10, 1, v58
	v_and_b32_e32 v17, 32, v10
	v_and_b32_e32 v18, 0x100, v67
	v_add3_u32 v15, 0, v15, v16
	v_add3_u32 v205, v15, v17, v18
	v_bitop3_b32 v15, v59, v66, s51 bitop3:0x28
	v_lshl_add_u32 v16, v46, 8, 0
	v_add_u32_e32 v217, v16, v15
	v_and_b32_e32 v15, 3, v52
	v_lshlrev_b32_e32 v16, 1, v52
	v_lshrrev_b32_e32 v17, 1, v52
	v_and_b32_e32 v16, 8, v16
	v_and_or_b32 v15, v17, 4, v15
	v_and_b32_e32 v17, 0x7ffff0, v52
	v_bfe_u32 v18, v67, 5, 3
	v_or3_b32 v16, v17, v16, v18
	v_lshlrev_b32_e32 v16, 9, v16
	v_lshlrev_b32_e32 v15, 6, v15
	v_and_b32_e32 v17, 48, v59
	v_add_co_u32_e32 v10, vcc, s86, v56
	v_or3_b32 v218, v16, v15, v17
	s_nop 0
	v_addc_co_u32_e32 v11, vcc, 0, v57, vcc
	v_add_u32_e32 v16, 0, v218
	global_load_dwordx4 v[10:13], v[10:11], off
	s_waitcnt vmcnt(5)
	ds_write_b128 v217, v[34:37]
	s_waitcnt vmcnt(4)
	ds_write_b128 v217, v[38:41] offset:8192
	s_waitcnt vmcnt(3)
	ds_write_b128 v16, v[42:45] offset:16384
	v_add_u32_e32 v16, 16, v52
	v_lshlrev_b32_e32 v19, 1, v16
	v_and_b32_e32 v19, 8, v19
	v_and_b32_e32 v16, 0x7ffff0, v16
	v_or3_b32 v16, v16, v19, v18
	v_lshlrev_b32_e32 v16, 9, v16
	v_or3_b32 v219, v16, v15, v17
	v_add_u32_e32 v16, 0, v219
	v_and_b32_e32 v14, 31, v58
	v_lshl_add_u32 v223, v14, 2, s92
	v_mov_b32_e32 v242, 0
	v_mov_b32_e32 v233, 0xf149f2ca
	s_waitcnt vmcnt(2)
	ds_write_b128 v16, v[2:5] offset:16384
	v_add_u32_e32 v2, 32, v52
	v_lshlrev_b32_e32 v3, 1, v2
	v_and_b32_e32 v3, 8, v3
	v_and_b32_e32 v2, 0x7ffff0, v2
	v_or3_b32 v2, v2, v3, v18
	v_lshlrev_b32_e32 v2, 9, v2
	v_or3_b32 v220, v2, v15, v17
	v_add_u32_e32 v2, 0, v220
	s_waitcnt vmcnt(1)
	ds_write_b128 v2, v[6:9] offset:16384
	v_add_u32_e32 v2, 48, v52
	v_lshlrev_b32_e32 v3, 1, v2
	v_and_b32_e32 v3, 8, v3
	v_and_b32_e32 v2, 0x7ffff0, v2
	v_or3_b32 v6, v2, v3, v18
	v_add_co_u32_e32 v2, vcc, s88, v56
	v_mov_b32_e32 v7, v1
	s_nop 0
	v_addc_co_u32_e32 v3, vcc, 0, v57, vcc
	v_add_co_u32_e32 v4, vcc, s56, v56
	v_mov_b32_e32 v8, v1
	s_nop 0
	v_addc_co_u32_e32 v5, vcc, 0, v57, vcc
	global_load_dwordx4 v[176:179], v[2:3], off
	global_load_dwordx4 v[180:183], v[4:5], off
	v_add_co_u32_e32 v2, vcc, s89, v56
	v_mov_b32_e32 v9, v1
	s_nop 0
	v_addc_co_u32_e32 v3, vcc, 0, v57, vcc
	v_add_co_u32_e32 v4, vcc, s58, v56
	s_mov_b64 s[44:45], 0
	s_nop 0
	v_addc_co_u32_e32 v5, vcc, 0, v57, vcc
	global_load_dwordx4 v[184:187], v[2:3], off
	global_load_dwordx4 v[188:191], v[4:5], off
	v_add_co_u32_e32 v2, vcc, s56, v50
	s_mov_b32 s33, 0
	s_nop 0
	v_addc_co_u32_e32 v3, vcc, 0, v51, vcc
	v_add_co_u32_e32 v4, vcc, s58, v50
	s_nop 1
	v_addc_co_u32_e32 v5, vcc, 0, v51, vcc
	global_load_dwordx4 v[192:195], v[2:3], off
	global_load_dwordx4 v[196:199], v[4:5], off
	v_lshlrev_b32_e32 v2, 9, v6
	v_or3_b32 v222, v2, v15, v17
	v_add_u32_e32 v2, 0, v222
	v_lshlrev_b32_e32 v3, 8, v14
	v_add_u32_e32 v224, 0, v3
	v_mov_b32_e32 v15, v1
	v_mov_b32_e32 v4, v1
	v_mov_b32_e32 v5, v1
	v_mov_b32_e32 v6, v1
	s_waitcnt vmcnt(6)
	ds_write_b128 v2, v[10:13] offset:16384
	v_ashrrev_i32_e32 v2, 1, v58
	v_and_b32_e32 v221, -16, v2
	v_bitop3_b32 v225, v2, v0, -16 bitop3:0x6c
	v_add_u32_e32 v0, 32, v221
	v_bitop3_b32 v226, v0, v59, s51 bitop3:0x78
	v_add_u32_e32 v0, 64, v221
	v_bitop3_b32 v227, v0, v59, s51 bitop3:0x78
	v_add_u32_e32 v0, 0x60, v221
	v_bitop3_b32 v228, v0, v59, s51 bitop3:0x78
	v_add_u32_e32 v0, 0x80, v221
	v_bitop3_b32 v229, v0, v59, s51 bitop3:0x78
	v_add_u32_e32 v0, 0xa0, v221
	v_bitop3_b32 v230, v0, v59, s51 bitop3:0x78
	v_add_u32_e32 v0, 0xc0, v221
	v_bitop3_b32 v231, v0, v59, s51 bitop3:0x78
	v_add_u32_e32 v0, 0xe0, v221
	v_bitop3_b32 v232, v0, v59, s51 bitop3:0x78
	v_add_u32_e32 v16, v225, v3
	v_add_u32_e32 v17, v226, v3
	v_add_u32_e32 v18, v227, v3
	v_add_u32_e32 v19, v228, v3
	v_add_u32_e32 v20, v229, v3
	v_add_u32_e32 v21, v230, v3
	v_add_u32_e32 v22, v231, v3
	v_add_u32_e32 v23, v232, v3
	v_lshl_add_u64 v[2:3], s[38:39], 0, v[54:55]
	v_lshlrev_b32_e32 v0, 4, v14
	v_lshl_add_u64 v[2:3], v[2:3], 0, v[0:1]
	v_and_b32_e32 v0, 15, v58
	v_lshl_add_u64 v[208:209], s[6:7], 0, v[2:3]
	v_lshl_add_u64 v[2:3], s[38:39], 0, v[48:49]
	v_lshlrev_b32_e32 v0, 4, v0
	v_lshl_add_u64 v[2:3], v[2:3], 0, v[0:1]
	v_mov_b32_e32 v14, v1
	v_lshl_add_u64 v[210:211], s[6:7], 0, v[2:3]
	v_mov_b32_e32 v0, v1
	v_mov_b32_e32 v2, v1
	v_mov_b32_e32 v3, v1
	v_mov_b32_e32 v10, v1
	v_mov_b32_e32 v11, v1
	v_mov_b32_e32 v12, v1
	v_mov_b32_e32 v13, v1
	v_add_u32_e32 v234, s91, v16
	v_add_u32_e32 v235, s91, v17
	v_add_u32_e32 v236, s91, v18
	v_add_u32_e32 v237, s91, v19
	v_add_u32_e32 v238, s91, v20
	v_add_u32_e32 v239, s91, v21
	v_add_u32_e32 v240, s91, v22
	v_add_u32_e32 v241, s91, v23
	v_mov_b64_e32 v[30:31], v[14:15]
	v_mov_b64_e32 v[46:47], v[14:15]
	v_mov_b64_e32 v[62:63], v[14:15]
	v_mov_b64_e32 v[78:79], v[14:15]
	v_mov_b64_e32 v[94:95], v[14:15]
	v_mov_b64_e32 v[110:111], v[14:15]
	v_mov_b64_e32 v[126:127], v[14:15]
	v_mov_b64_e32 v[142:143], v[14:15]
	v_mov_b64_e32 v[28:29], v[12:13]
	v_mov_b64_e32 v[26:27], v[10:11]
	v_mov_b64_e32 v[24:25], v[8:9]
	v_mov_b64_e32 v[22:23], v[6:7]
	v_mov_b64_e32 v[20:21], v[4:5]
	v_mov_b64_e32 v[18:19], v[2:3]
	v_mov_b64_e32 v[16:17], v[0:1]
	v_mov_b64_e32 v[44:45], v[12:13]
	v_mov_b64_e32 v[42:43], v[10:11]
	v_mov_b64_e32 v[40:41], v[8:9]
	v_mov_b64_e32 v[38:39], v[6:7]
	v_mov_b64_e32 v[36:37], v[4:5]
	v_mov_b64_e32 v[34:35], v[2:3]
	v_mov_b64_e32 v[32:33], v[0:1]
	v_mov_b64_e32 v[60:61], v[12:13]
	v_mov_b64_e32 v[58:59], v[10:11]
	v_mov_b64_e32 v[56:57], v[8:9]
	v_mov_b64_e32 v[54:55], v[6:7]
	v_mov_b64_e32 v[52:53], v[4:5]
	v_mov_b64_e32 v[50:51], v[2:3]
	v_mov_b64_e32 v[48:49], v[0:1]
	v_mov_b64_e32 v[76:77], v[12:13]
	v_mov_b64_e32 v[74:75], v[10:11]
	v_mov_b64_e32 v[72:73], v[8:9]
	v_mov_b64_e32 v[70:71], v[6:7]
	v_mov_b64_e32 v[68:69], v[4:5]
	v_mov_b64_e32 v[66:67], v[2:3]
	v_mov_b64_e32 v[64:65], v[0:1]
	v_mov_b64_e32 v[92:93], v[12:13]
	v_mov_b64_e32 v[90:91], v[10:11]
	v_mov_b64_e32 v[88:89], v[8:9]
	v_mov_b64_e32 v[86:87], v[6:7]
	v_mov_b64_e32 v[84:85], v[4:5]
	v_mov_b64_e32 v[82:83], v[2:3]
	v_mov_b64_e32 v[80:81], v[0:1]
	v_mov_b64_e32 v[108:109], v[12:13]
	v_mov_b64_e32 v[106:107], v[10:11]
	v_mov_b64_e32 v[104:105], v[8:9]
	v_mov_b64_e32 v[102:103], v[6:7]
	v_mov_b64_e32 v[100:101], v[4:5]
	v_mov_b64_e32 v[98:99], v[2:3]
	v_mov_b64_e32 v[96:97], v[0:1]
	v_mov_b64_e32 v[124:125], v[12:13]
	v_mov_b64_e32 v[122:123], v[10:11]
	v_mov_b64_e32 v[120:121], v[8:9]
	v_mov_b64_e32 v[118:119], v[6:7]
	v_mov_b64_e32 v[116:117], v[4:5]
	v_mov_b64_e32 v[114:115], v[2:3]
	v_mov_b64_e32 v[112:113], v[0:1]
	v_mov_b64_e32 v[140:141], v[12:13]
	v_mov_b64_e32 v[138:139], v[10:11]
	v_mov_b64_e32 v[136:137], v[8:9]
	v_mov_b64_e32 v[134:135], v[6:7]
	v_mov_b64_e32 v[132:133], v[4:5]
	v_mov_b64_e32 v[130:131], v[2:3]
	v_mov_b64_e32 v[128:129], v[0:1]
